# HGRN2 output pass: run-prefix loads issued as a rolling pipeline (80 loads in flight) instead of 4 dependent round trips per run
# baseline (speedup 1.0000x reference)
; __device__ __forceinline__ int crow(int r,int hi){return (r&3)+8*(r>>2)+4*hi;}
; #define LAS __attribute__((address_space(3)))
; __device__ __forceinline__ int crow(int reg, int h) { return (reg & 3) + 8 * (reg >> 2) + 4 * h; }
; template <bool OUT>
; __device__ __forceinline__ void item(LAS unsigned char* L, const u16* __restrict__ H, int it, const float* __restrict__ lbv, float* Send, float* Drun, const float* __restrict__ outg, u16* MIX, const int tid, const float* Sst = nullptr) {
;     const int  lane = tid & 63, w = __builtin_amdgcn_readfirstlane(tid >> 6), r = lane & 31, h = lane >> 5;
;     const int tt = w & 1, vt = w >> 1;
;     const int bh = it >> 4, run = it & 15, b = bh >> 2, hh = bh & 3;
;     const int kd = tid & 127, seg = tid >> 7;
;     const size_t row0 = (size_t)b * 8192 + (size_t)run * 512;
;     const float lb = lbv[hh * 128 + kd];
;     LAS float* TOT = (LAS float*)(L + O_TOT); LAS float* DEC = (LAS float*)(L + O_DEC); LAS float* OST = (LAS float*)(L + O_OST);
;     f32x16 S[4];
; #pragma unroll
;     for (int k = 0; k < 4; ++k) S[k] = f32x16{};
;     if (OUT && run > 0) {
;         if (Sst) {
; #pragma unroll
;             for (int k = 0; k < 4; ++k)
; #pragma unroll
;                 for (int i = 0; i < 16; ++i) S[k][i] = Sst[((((size_t)it * 4 + vt) * 4 + k) * 16 + i) * 64 + lane];
;         } else {
;             for (int rp = 0; rp < run; ++rp) { const int ip = bh * 16 + rp;
; #pragma unroll
;                 for (int k = 0; k < 4; ++k)
; #pragma unroll
;                     for (int i = 0; i < 16; ++i) S[k][i] = Drun[ip * 128 + 32 * k + crow(i, h)] * S[k][i] + Send[((((size_t)ip * 4 + vt) * 4 + k) * 16 + i) * 64 + lane];
.LBB0_218:
	v_readlane_b32 s0, v253, 25
	v_mbcnt_lo_u32_b32 v0, -1, 0
	v_mbcnt_hi_u32_b32 v0, -1, v0
	s_lshl_b32 s2, s52, 3
	s_and_b32 s4, s2, 0x180
	v_add_u32_e32 v93, s0, v0
	s_and_b32 s6, s49, 15
	v_and_b32_e32 v95, 0x7f, v93
	v_or_b32_e32 v0, s4, v95
	v_lshlrev_b32_e32 v0, 2, v0
	global_load_dword v178, v0, s[50:51]
	v_readfirstlane_b32 s26, v93
	s_and_b32 s5, s52, 15
	v_and_b32_e32 v0, 63, v93
	v_bfe_u32 v94, v93, 5, 1
	s_ashr_i32 s10, s26, 7
	s_cmp_lg_u32 s5, 0
	v_lshlrev_b32_e32 v80, 2, v0
	v_lshlrev_b32_e32 v82, 2, v94
	s_cbranch_scc0 .LBB0_222
	s_and_b32 s2, s52, -16
	s_ashr_i32 s3, s2, 31
	s_lshl_b32 s7, s52, 7
	s_ashr_i32 s11, s10, 31
	s_lshl_b64 s[2:3], s[2:3], 16
	s_and_b32 s12, s7, 0xfffff800
	s_lshl_b32 s7, s6, 16
	s_lshl_b64 s[8:9], s[10:11], 14
	s_add_u32 s2, s2, s8
	s_addc_u32 s3, s3, s9
	s_add_u32 s2, s62, s2
	v_lshlrev_b32_e32 v92, 2, v94
	v_mov_b32_e32 v81, v1
	s_addc_u32 s3, s63, s3
	v_mov_b32_e32 v16, 0
	v_readlane_b32 s0, v253, 61
	v_lshl_add_u64 v[2:3], s[2:3], 0, v[80:81]
	v_or_b32_e32 v4, s12, v92
	s_mov_b64 s[2:3], 0
	v_mov_b32_e32 v17, v16
	v_mov_b32_e32 v18, v16
	v_mov_b32_e32 v19, v16
	v_mov_b32_e32 v20, v16
	v_mov_b32_e32 v21, v16
	v_mov_b32_e32 v22, v16
	v_mov_b32_e32 v23, v16
	v_mov_b32_e32 v24, v16
	v_mov_b32_e32 v25, v16
	v_mov_b32_e32 v26, v16
	v_mov_b32_e32 v27, v16
	v_mov_b32_e32 v28, v16
	v_mov_b32_e32 v29, v16
	v_mov_b32_e32 v30, v16
	v_mov_b32_e32 v31, v16
	v_mov_b32_e32 v32, v16
	v_mov_b32_e32 v33, v16
	v_mov_b32_e32 v34, v16
	v_mov_b32_e32 v35, v16
	v_mov_b32_e32 v36, v16
	v_mov_b32_e32 v37, v16
	v_mov_b32_e32 v38, v16
	v_mov_b32_e32 v39, v16
	v_mov_b32_e32 v40, v16
	v_mov_b32_e32 v41, v16
	v_mov_b32_e32 v42, v16
	v_mov_b32_e32 v43, v16
	v_mov_b32_e32 v44, v16
	v_mov_b32_e32 v45, v16
	v_mov_b32_e32 v46, v16
	v_mov_b32_e32 v47, v16
	v_mov_b32_e32 v48, v16
	v_mov_b32_e32 v49, v16
	v_mov_b32_e32 v50, v16
	v_mov_b32_e32 v51, v16
	v_mov_b32_e32 v52, v16
	v_mov_b32_e32 v53, v16
	v_mov_b32_e32 v54, v16
	v_mov_b32_e32 v55, v16
	v_mov_b32_e32 v56, v16
	v_mov_b32_e32 v57, v16
	v_mov_b32_e32 v58, v16
	v_mov_b32_e32 v59, v16
	v_mov_b32_e32 v60, v16
	v_mov_b32_e32 v61, v16
	v_mov_b32_e32 v62, v16
	v_mov_b32_e32 v63, v16
	v_mov_b32_e32 v64, v16
	v_mov_b32_e32 v65, v16
	s_waitcnt vmcnt(1)
	v_mov_b32_e32 v66, v16
	v_mov_b32_e32 v67, v16
	v_mov_b32_e32 v68, v16
	v_mov_b32_e32 v69, v16
	v_mov_b32_e32 v70, v16
	v_mov_b32_e32 v71, v16
	v_mov_b32_e32 v72, v16
	v_mov_b32_e32 v73, v16
	v_mov_b32_e32 v74, v16
	v_mov_b32_e32 v75, v16
	v_mov_b32_e32 v76, v16
	v_mov_b32_e32 v77, v16
	v_mov_b32_e32 v78, v16
	v_mov_b32_e32 v79, v16
	v_readlane_b32 s1, v253, 62
	s_mov_b32 s12, 0x1a000000
	s_mov_b32 s13, 0
	s_mov_b32 s14, 0x1a001000
	s_mov_b32 s15, 0
	s_mov_b32 s16, 0x1a002000
	s_mov_b32 s17, 0
	s_mov_b32 s18, 0x1a003000
	s_mov_b32 s19, 0
	v_lshl_add_u64 v[10:11], v[2:3], 0, s[2:3]
	v_ashrrev_i32_e32 v5, 31, v4
	v_lshl_add_u64 v[6:7], v[4:5], 2, s[0:1]
	v_lshl_add_u64 v[8:9], v[10:11], 0, s[12:13]
	global_load_dwordx4 v[180:183], v[6:7], off
	global_load_dwordx4 v[184:187], v[6:7], off offset:32
	global_load_dwordx4 v[188:191], v[6:7], off offset:64
	global_load_dwordx4 v[192:195], v[6:7], off offset:96
	global_load_dword v96, v[8:9], off
	global_load_dword v97, v[8:9], off offset:256
	global_load_dword v98, v[8:9], off offset:512
	global_load_dword v99, v[8:9], off offset:768
	global_load_dword v100, v[8:9], off offset:1024
	global_load_dword v101, v[8:9], off offset:1280
	global_load_dword v102, v[8:9], off offset:1536
	global_load_dword v103, v[8:9], off offset:1792
	global_load_dword v104, v[8:9], off offset:2048
	global_load_dword v105, v[8:9], off offset:2304
	global_load_dword v106, v[8:9], off offset:2560
	global_load_dword v107, v[8:9], off offset:2816
	global_load_dword v108, v[8:9], off offset:3072
	global_load_dword v109, v[8:9], off offset:3328
	global_load_dword v110, v[8:9], off offset:3584
	global_load_dword v111, v[8:9], off offset:3840
	v_lshl_add_u64 v[8:9], v[10:11], 0, s[14:15]
	global_load_dwordx4 v[196:199], v[6:7], off offset:128
	global_load_dwordx4 v[200:203], v[6:7], off offset:160
	global_load_dwordx4 v[204:207], v[6:7], off offset:192
	global_load_dwordx4 v[208:211], v[6:7], off offset:224
	global_load_dword v112, v[8:9], off
	global_load_dword v113, v[8:9], off offset:256
	global_load_dword v114, v[8:9], off offset:512
	global_load_dword v115, v[8:9], off offset:768
	global_load_dword v116, v[8:9], off offset:1024
	global_load_dword v117, v[8:9], off offset:1280
	global_load_dword v118, v[8:9], off offset:1536
	global_load_dword v119, v[8:9], off offset:1792
	global_load_dword v120, v[8:9], off offset:2048
	global_load_dword v121, v[8:9], off offset:2304
	global_load_dword v122, v[8:9], off offset:2560
	global_load_dword v123, v[8:9], off offset:2816
	global_load_dword v124, v[8:9], off offset:3072
	global_load_dword v125, v[8:9], off offset:3328
	global_load_dword v126, v[8:9], off offset:3584
	global_load_dword v127, v[8:9], off offset:3840
	v_lshl_add_u64 v[8:9], v[10:11], 0, s[16:17]
	global_load_dwordx4 v[212:215], v[6:7], off offset:256
	global_load_dwordx4 v[216:219], v[6:7], off offset:288
	global_load_dwordx4 v[220:223], v[6:7], off offset:320
	global_load_dwordx4 v[224:227], v[6:7], off offset:352
	global_load_dword v128, v[8:9], off
	global_load_dword v129, v[8:9], off offset:256
	global_load_dword v130, v[8:9], off offset:512
	global_load_dword v131, v[8:9], off offset:768
	global_load_dword v132, v[8:9], off offset:1024
	global_load_dword v133, v[8:9], off offset:1280
	global_load_dword v134, v[8:9], off offset:1536
	global_load_dword v135, v[8:9], off offset:1792
; __device__ __forceinline__ int crow(int r,int hi){return (r&3)+8*(r>>2)+4*hi;}
; __device__ __forceinline__ int crow(int reg, int h) { return (reg & 3) + 8 * (reg >> 2) + 4 * h; }
; template <bool OUT>
; __device__ __forceinline__ void item(LAS unsigned char* L, const u16* __restrict__ H, int it, const float* __restrict__ lbv, float* Send, float* Drun, const float* __restrict__ outg, u16* MIX, const int tid, const float* Sst = nullptr) {
;     ...
;             for (int rp = 0; rp < run; ++rp) { const int ip = bh * 16 + rp;
; #pragma unroll
;                 for (int k = 0; k < 4; ++k)
; #pragma unroll
;                     for (int i = 0; i < 16; ++i) S[k][i] = Drun[ip * 128 + 32 * k + crow(i, h)] * S[k][i] + Send[((((size_t)ip * 4 + vt) * 4 + k) * 16 + i) * 64 + lane];
	global_load_dword v136, v[8:9], off offset:2048
	global_load_dword v137, v[8:9], off offset:2304
	global_load_dword v138, v[8:9], off offset:2560
	global_load_dword v139, v[8:9], off offset:2816
	global_load_dword v140, v[8:9], off offset:3072
	global_load_dword v141, v[8:9], off offset:3328
	global_load_dword v142, v[8:9], off offset:3584
	global_load_dword v143, v[8:9], off offset:3840
	v_lshl_add_u64 v[8:9], v[10:11], 0, s[18:19]
	global_load_dwordx4 v[228:231], v[6:7], off offset:384
	global_load_dwordx4 v[232:235], v[6:7], off offset:416
	global_load_dwordx4 v[236:239], v[6:7], off offset:448
	global_load_dwordx4 v[240:243], v[6:7], off offset:480
	global_load_dword v144, v[8:9], off
	global_load_dword v145, v[8:9], off offset:256
	global_load_dword v146, v[8:9], off offset:512
	global_load_dword v147, v[8:9], off offset:768
	global_load_dword v148, v[8:9], off offset:1024
	global_load_dword v149, v[8:9], off offset:1280
	global_load_dword v150, v[8:9], off offset:1536
	global_load_dword v151, v[8:9], off offset:1792
	global_load_dword v152, v[8:9], off offset:2048
	global_load_dword v153, v[8:9], off offset:2304
	global_load_dword v154, v[8:9], off offset:2560
	global_load_dword v155, v[8:9], off offset:2816
	global_load_dword v156, v[8:9], off offset:3072
	global_load_dword v157, v[8:9], off offset:3328
	global_load_dword v158, v[8:9], off offset:3584
	global_load_dword v159, v[8:9], off offset:3840
; __device__ __forceinline__ int crow(int r,int hi){return (r&3)+8*(r>>2)+4*hi;}
; __device__ __forceinline__ int crow(int reg, int h) { return (reg & 3) + 8 * (reg >> 2) + 4 * h; }
; template <bool OUT>
; __device__ __forceinline__ void item(LAS unsigned char* L, const u16* __restrict__ H, int it, const float* __restrict__ lbv, float* Send, float* Drun, const float* __restrict__ outg, u16* MIX, const int tid, const float* Sst = nullptr) {
;     ...
;             for (int rp = 0; rp < run; ++rp) { const int ip = bh * 16 + rp;
; #pragma unroll
;                 for (int k = 0; k < 4; ++k)
; #pragma unroll
;                     for (int i = 0; i < 16; ++i) S[k][i] = Drun[ip * 128 + 32 * k + crow(i, h)] * S[k][i] + Send[((((size_t)ip * 4 + vt) * 4 + k) * 16 + i) * 64 + lane];
.LBB0_220:
	s_add_u32 s2, s2, 0x10000
	s_addc_u32 s3, s3, 0
	v_add_u32_e32 v4, 0x80, v4
	v_lshl_add_u64 v[10:11], v[2:3], 0, s[2:3]
	v_ashrrev_i32_e32 v5, 31, v4
	v_lshl_add_u64 v[6:7], v[4:5], 2, s[0:1]
	s_waitcnt vmcnt(60)
	v_pk_fma_f32 v[16:17], v[16:17], v[180:181], v[96:97]
	v_pk_fma_f32 v[18:19], v[18:19], v[182:183], v[98:99]
	v_pk_fma_f32 v[20:21], v[20:21], v[184:185], v[100:101]
	v_pk_fma_f32 v[22:23], v[22:23], v[186:187], v[102:103]
	v_pk_fma_f32 v[24:25], v[24:25], v[188:189], v[104:105]
	v_pk_fma_f32 v[26:27], v[26:27], v[190:191], v[106:107]
	v_pk_fma_f32 v[28:29], v[28:29], v[192:193], v[108:109]
	v_pk_fma_f32 v[30:31], v[30:31], v[194:195], v[110:111]
	v_lshl_add_u64 v[8:9], v[10:11], 0, s[12:13]
	global_load_dwordx4 v[180:183], v[6:7], off
	global_load_dwordx4 v[184:187], v[6:7], off offset:32
	global_load_dwordx4 v[188:191], v[6:7], off offset:64
	global_load_dwordx4 v[192:195], v[6:7], off offset:96
	global_load_dword v96, v[8:9], off
	global_load_dword v97, v[8:9], off offset:256
	global_load_dword v98, v[8:9], off offset:512
	global_load_dword v99, v[8:9], off offset:768
	global_load_dword v100, v[8:9], off offset:1024
	global_load_dword v101, v[8:9], off offset:1280
	global_load_dword v102, v[8:9], off offset:1536
	global_load_dword v103, v[8:9], off offset:1792
	global_load_dword v104, v[8:9], off offset:2048
	global_load_dword v105, v[8:9], off offset:2304
	global_load_dword v106, v[8:9], off offset:2560
	global_load_dword v107, v[8:9], off offset:2816
	global_load_dword v108, v[8:9], off offset:3072
	global_load_dword v109, v[8:9], off offset:3328
	global_load_dword v110, v[8:9], off offset:3584
	global_load_dword v111, v[8:9], off offset:3840
	s_waitcnt vmcnt(60)
	v_pk_fma_f32 v[32:33], v[32:33], v[196:197], v[112:113]
	v_pk_fma_f32 v[34:35], v[34:35], v[198:199], v[114:115]
	v_pk_fma_f32 v[36:37], v[36:37], v[200:201], v[116:117]
	v_pk_fma_f32 v[38:39], v[38:39], v[202:203], v[118:119]
	v_pk_fma_f32 v[40:41], v[40:41], v[204:205], v[120:121]
	v_pk_fma_f32 v[42:43], v[42:43], v[206:207], v[122:123]
	v_pk_fma_f32 v[44:45], v[44:45], v[208:209], v[124:125]
	v_pk_fma_f32 v[46:47], v[46:47], v[210:211], v[126:127]
	v_lshl_add_u64 v[8:9], v[10:11], 0, s[14:15]
	global_load_dwordx4 v[196:199], v[6:7], off offset:128
	global_load_dwordx4 v[200:203], v[6:7], off offset:160
	global_load_dwordx4 v[204:207], v[6:7], off offset:192
	global_load_dwordx4 v[208:211], v[6:7], off offset:224
	global_load_dword v112, v[8:9], off
	global_load_dword v113, v[8:9], off offset:256
	global_load_dword v114, v[8:9], off offset:512
	global_load_dword v115, v[8:9], off offset:768
	global_load_dword v116, v[8:9], off offset:1024
	global_load_dword v117, v[8:9], off offset:1280
	global_load_dword v118, v[8:9], off offset:1536
	global_load_dword v119, v[8:9], off offset:1792
	global_load_dword v120, v[8:9], off offset:2048
	global_load_dword v121, v[8:9], off offset:2304
	global_load_dword v122, v[8:9], off offset:2560
	global_load_dword v123, v[8:9], off offset:2816
	global_load_dword v124, v[8:9], off offset:3072
	global_load_dword v125, v[8:9], off offset:3328
	global_load_dword v126, v[8:9], off offset:3584
	global_load_dword v127, v[8:9], off offset:3840
	s_waitcnt vmcnt(60)
	v_pk_fma_f32 v[48:49], v[48:49], v[212:213], v[128:129]
	v_pk_fma_f32 v[50:51], v[50:51], v[214:215], v[130:131]
	v_pk_fma_f32 v[52:53], v[52:53], v[216:217], v[132:133]
	v_pk_fma_f32 v[54:55], v[54:55], v[218:219], v[134:135]
	v_pk_fma_f32 v[56:57], v[56:57], v[220:221], v[136:137]
	v_pk_fma_f32 v[58:59], v[58:59], v[222:223], v[138:139]
	v_pk_fma_f32 v[60:61], v[60:61], v[224:225], v[140:141]
	v_pk_fma_f32 v[62:63], v[62:63], v[226:227], v[142:143]
	v_lshl_add_u64 v[8:9], v[10:11], 0, s[16:17]
	global_load_dwordx4 v[212:215], v[6:7], off offset:256
	global_load_dwordx4 v[216:219], v[6:7], off offset:288
	global_load_dwordx4 v[220:223], v[6:7], off offset:320
	global_load_dwordx4 v[224:227], v[6:7], off offset:352
	global_load_dword v128, v[8:9], off
	global_load_dword v129, v[8:9], off offset:256
	global_load_dword v130, v[8:9], off offset:512
	global_load_dword v131, v[8:9], off offset:768
	global_load_dword v132, v[8:9], off offset:1024
	global_load_dword v133, v[8:9], off offset:1280
	global_load_dword v134, v[8:9], off offset:1536
	global_load_dword v135, v[8:9], off offset:1792
	global_load_dword v136, v[8:9], off offset:2048
	global_load_dword v137, v[8:9], off offset:2304
	global_load_dword v138, v[8:9], off offset:2560
	global_load_dword v139, v[8:9], off offset:2816
	global_load_dword v140, v[8:9], off offset:3072
	global_load_dword v141, v[8:9], off offset:3328
	global_load_dword v142, v[8:9], off offset:3584
	global_load_dword v143, v[8:9], off offset:3840
	s_waitcnt vmcnt(60)
	v_pk_fma_f32 v[64:65], v[64:65], v[228:229], v[144:145]
	v_pk_fma_f32 v[66:67], v[66:67], v[230:231], v[146:147]
	v_pk_fma_f32 v[68:69], v[68:69], v[232:233], v[148:149]
	v_pk_fma_f32 v[70:71], v[70:71], v[234:235], v[150:151]
	v_pk_fma_f32 v[72:73], v[72:73], v[236:237], v[152:153]
	v_pk_fma_f32 v[74:75], v[74:75], v[238:239], v[154:155]
	v_pk_fma_f32 v[76:77], v[76:77], v[240:241], v[156:157]
	v_pk_fma_f32 v[78:79], v[78:79], v[242:243], v[158:159]
	v_lshl_add_u64 v[8:9], v[10:11], 0, s[18:19]
	global_load_dwordx4 v[228:231], v[6:7], off offset:384
	global_load_dwordx4 v[232:235], v[6:7], off offset:416
	global_load_dwordx4 v[236:239], v[6:7], off offset:448
	global_load_dwordx4 v[240:243], v[6:7], off offset:480
	global_load_dword v144, v[8:9], off
	global_load_dword v145, v[8:9], off offset:256
	global_load_dword v146, v[8:9], off offset:512
	global_load_dword v147, v[8:9], off offset:768
	global_load_dword v148, v[8:9], off offset:1024
	global_load_dword v149, v[8:9], off offset:1280
	global_load_dword v150, v[8:9], off offset:1536
	global_load_dword v151, v[8:9], off offset:1792
	global_load_dword v152, v[8:9], off offset:2048
	global_load_dword v153, v[8:9], off offset:2304
	global_load_dword v154, v[8:9], off offset:2560
	global_load_dword v155, v[8:9], off offset:2816
	global_load_dword v156, v[8:9], off offset:3072
	global_load_dword v157, v[8:9], off offset:3328
	global_load_dword v158, v[8:9], off offset:3584
	global_load_dword v159, v[8:9], off offset:3840
	s_cmp_lg_u32 s7, s2
	s_cbranch_scc1 .LBB0_220
	s_waitcnt vmcnt(0)
	s_mov_b64 s[2:3], 0
	s_branch .LBB0_223
